# on top of v25: HGRN2 output phase per-chunk rmsnorm partial sums: the four cross-lane reductions are interleaved (2 LDS crossbar round trips instead of 8 serialized ones)
# baseline (speedup 1.0000x reference)
; #define LAS __attribute__((address_space(3)))
; __device__ __forceinline__ unsigned pkbf(float lo, float hi) { const f32x2_t v = {lo, hi}; const bf16x2_t b = __builtin_convertvector(v, bf16x2_t); return __builtin_bit_cast(unsigned, b); }
; #define MFMA16(a, b, c) __builtin_amdgcn_mfma_f32_16x16x32_bf16((a), (b), (c), 0, 0, 0)
; __device__ __forceinline__ void hgrn_r3(const GAS bf16* proj, const GAS float* RU, const GAS float* RD, GAS bf16* y, int TOKG, const GAS float* ogain, unsigned char* lds, int tid, int lane, int wave, int bid, int G) {
;     ...
;                   const int t = 16 * tt + fr, s0 = 16 * ss + 4 * fq;
;                   v2u w; w.x = pkbf(s0 <= t ? a[0] : 0.f, s0 + 1 <= t ? a[1] : 0.f); w.y = pkbf(s0 + 2 <= t ? a[2] : 0.f, s0 + 3 <= t ? a[3] : 0.f);
;                   *(LAS v2u*)(L + H3_AM + t * HS + s0 * 2) = w; } }
;             f32x4h acc[4];
; #pragma unroll
;             for (int t2 = 0; t2 < 4; ++t2) acc[t2] = (f32x4h){0.f, 0.f, 0.f, 0.f};
; #pragma unroll
;             for (int t2 = 0; t2 < 4; ++t2)
; #pragma unroll
;                 for (int ks = 0; ks < 4; ++ks) { const bf16x8 qf = *(const LAS bf16x8*)(L + H3_QH + (16 * t2 + fr) * HQS + (32 * ks + 8 * fq) * 2); acc[t2] = MFMA16(sf[ks], qf, acc[t2]); }
;             bf16x8 vf[2];
; #pragma unroll
;             for (int ks = 0; ks < 2; ++ks) vf[ks] = *(const LAS bf16x8*)(L + H3_VT + (16 * wave + fr) * HS + (32 * ks + 8 * fq) * 2);
; #pragma unroll
;             for (int nk = 0; nk < 8; ++nk) { const f32x4h dk = *(const LAS f32x4h*)(decl + 16 * nk + 4 * fq); Sm[nk] = Sm[nk] * dk;
; #pragma unroll
;                 for (int ks = 0; ks < 2; ++ks) { const bf16x8 kf = *(const LAS bf16x8*)(L + H3_KT + (16 * nk + fr) * HS + (32 * ks + 8 * fq) * 2); Sm[nk] = MFMA16(kf, vf[ks], Sm[nk]); } }
;             __syncthreads();
.LBB0_392:
	s_nop 7
	v_cndmask_b32_e64 v52, v52, 0, s[30:31]
	v_cndmask_b32_e64 v53, 0, v53, s[34:35]
	v_cvt_pk_bf16_f32 v52, v52, v53
	v_cndmask_b32_e64 v53, v54, 0, s[36:37]
	v_cndmask_b32_e64 v54, v55, 0, s[38:39]
	v_cvt_pk_bf16_f32 v53, v53, v54
	ds_write_b64 v128, v[52:53]
	ds_read_b128 v[214:217], v129
	ds_read_b128 v[218:221], v129 offset:64
	ds_read_b128 v[222:225], v129 offset:128
	ds_read_b128 v[226:229], v129 offset:192
	ds_read_b128 v[230:233], v129 offset:4352
	ds_read_b128 v[64:67], v129 offset:4416
	s_waitcnt lgkmcnt(5)
	v_mfma_f32_16x16x32_bf16 v[52:55], v[48:51], v[214:217], 0
	ds_read_b128 v[214:217], v129 offset:4480
	s_waitcnt lgkmcnt(5)
	v_mfma_f32_16x16x32_bf16 v[52:55], v[44:47], v[218:221], v[52:55]
	ds_read_b128 v[218:221], v129 offset:4544
	s_waitcnt lgkmcnt(5)
	v_mfma_f32_16x16x32_bf16 v[52:55], v[40:43], v[222:225], v[52:55]
	ds_read_b128 v[222:225], v129 offset:8704
	s_waitcnt lgkmcnt(5)
	v_mfma_f32_16x16x32_bf16 v[52:55], v[36:39], v[226:229], v[52:55]
	ds_read_b128 v[226:229], v129 offset:8768
	s_waitcnt lgkmcnt(5)
	v_mfma_f32_16x16x32_bf16 v[56:59], v[48:51], v[230:233], 0
	ds_read_b128 v[230:233], v129 offset:8832
	s_waitcnt lgkmcnt(5)
	v_mfma_f32_16x16x32_bf16 v[56:59], v[44:47], v[64:67], v[56:59]
	ds_read_b128 v[64:67], v129 offset:8896
	s_waitcnt lgkmcnt(5)
	v_mfma_f32_16x16x32_bf16 v[56:59], v[40:43], v[214:217], v[56:59]
	ds_read_b128 v[214:217], v129 offset:13056
	s_waitcnt lgkmcnt(5)
	v_mfma_f32_16x16x32_bf16 v[56:59], v[36:39], v[218:221], v[56:59]
	ds_read_b128 v[218:221], v129 offset:13120
	s_waitcnt lgkmcnt(5)
	v_mfma_f32_16x16x32_bf16 v[60:63], v[48:51], v[222:225], 0
	ds_read_b128 v[222:225], v129 offset:13184
	s_waitcnt lgkmcnt(5)
	v_mfma_f32_16x16x32_bf16 v[60:63], v[44:47], v[226:229], v[60:63]
	ds_read_b128 v[226:229], v129 offset:13248
	s_waitcnt lgkmcnt(5)
	v_mfma_f32_16x16x32_bf16 v[60:63], v[40:43], v[230:233], v[60:63]
	s_waitcnt lgkmcnt(4)
	v_mfma_f32_16x16x32_bf16 v[60:63], v[36:39], v[64:67], v[60:63]
	s_waitcnt lgkmcnt(3)
	v_mfma_f32_16x16x32_bf16 v[48:51], v[48:51], v[214:217], 0
	s_waitcnt lgkmcnt(2)
	v_mfma_f32_16x16x32_bf16 v[44:47], v[44:47], v[218:221], v[48:51]
	s_waitcnt lgkmcnt(1)
	v_mfma_f32_16x16x32_bf16 v[40:43], v[40:43], v[222:225], v[44:47]
	s_waitcnt lgkmcnt(0)
	v_mfma_f32_16x16x32_bf16 v[40:43], v[36:39], v[226:229], v[40:43]
	s_nop 3
	ds_read_b128 v[44:47], v130 offset:52224
	ds_read_b128 v[36:39], v130 offset:52288
	ds_read_b128 v[48:51], v117
	ds_read_b128 v[214:217], v131
	ds_read_b128 v[218:221], v131 offset:64
	ds_read_b128 v[222:225], v117 offset:64
	ds_read_b128 v[226:229], v131 offset:2304
	ds_read_b128 v[230:233], v131 offset:2368
	s_waitcnt lgkmcnt(4)
	v_pk_mul_f32 v[22:23], v[22:23], v[50:51]
	v_pk_mul_f32 v[20:21], v[20:21], v[48:49]
	s_nop 1
	v_mfma_f32_16x16x32_bf16 v[20:23], v[214:217], v[44:47], v[20:23]
	s_waitcnt lgkmcnt(3)
	v_mfma_f32_16x16x32_bf16 v[20:23], v[218:221], v[36:39], v[20:23]
	ds_read_b128 v[48:51], v117 offset:128
	ds_read_b128 v[214:217], v131 offset:4608
	ds_read_b128 v[218:221], v131 offset:4672
	s_waitcnt lgkmcnt(4)
	v_pk_mul_f32 v[6:7], v[6:7], v[224:225]
	v_pk_mul_f32 v[4:5], v[4:5], v[222:223]
	s_nop 1
	v_mfma_f32_16x16x32_bf16 v[4:7], v[226:229], v[44:47], v[4:7]
	s_waitcnt lgkmcnt(3)
	v_mfma_f32_16x16x32_bf16 v[4:7], v[230:233], v[36:39], v[4:7]
	ds_read_b128 v[222:225], v117 offset:192
	ds_read_b128 v[226:229], v131 offset:6912
	ds_read_b128 v[230:233], v131 offset:6976
	s_waitcnt lgkmcnt(4)
	v_pk_mul_f32 v[18:19], v[18:19], v[50:51]
	v_pk_mul_f32 v[16:17], v[16:17], v[48:49]
	s_nop 1
	v_mfma_f32_16x16x32_bf16 v[16:19], v[214:217], v[44:47], v[16:19]
	s_waitcnt lgkmcnt(3)
	v_mfma_f32_16x16x32_bf16 v[16:19], v[218:221], v[36:39], v[16:19]
	ds_read_b128 v[48:51], v117 offset:256
	ds_read_b128 v[214:217], v131 offset:9216
	ds_read_b128 v[218:221], v131 offset:9280
	s_waitcnt lgkmcnt(4)
	v_pk_mul_f32 v[10:11], v[10:11], v[224:225]
	v_pk_mul_f32 v[8:9], v[8:9], v[222:223]
	s_nop 1
	v_mfma_f32_16x16x32_bf16 v[8:11], v[226:229], v[44:47], v[8:11]
	s_waitcnt lgkmcnt(3)
	v_mfma_f32_16x16x32_bf16 v[8:11], v[230:233], v[36:39], v[8:11]
	ds_read_b128 v[222:225], v117 offset:320
	ds_read_b128 v[226:229], v131 offset:11520
	ds_read_b128 v[230:233], v131 offset:11584
	s_waitcnt lgkmcnt(4)
	v_pk_mul_f32 v[26:27], v[26:27], v[50:51]
	v_pk_mul_f32 v[24:25], v[24:25], v[48:49]
	s_nop 1
	v_mfma_f32_16x16x32_bf16 v[24:27], v[214:217], v[44:47], v[24:27]
	s_waitcnt lgkmcnt(3)
	v_mfma_f32_16x16x32_bf16 v[24:27], v[218:221], v[36:39], v[24:27]
	ds_read_b128 v[48:51], v117 offset:384
	ds_read_b128 v[214:217], v131 offset:13824
	ds_read_b128 v[218:221], v131 offset:13888
	s_waitcnt lgkmcnt(4)
	v_pk_mul_f32 v[14:15], v[14:15], v[224:225]
	v_pk_mul_f32 v[12:13], v[12:13], v[222:223]
	s_nop 1
	v_mfma_f32_16x16x32_bf16 v[12:15], v[226:229], v[44:47], v[12:15]
	s_waitcnt lgkmcnt(3)
	v_mfma_f32_16x16x32_bf16 v[12:15], v[230:233], v[36:39], v[12:15]
	ds_read_b128 v[222:225], v117 offset:448
	ds_read_b128 v[226:229], v131 offset:16128
	ds_read_b128 v[230:233], v131 offset:16192
	s_waitcnt lgkmcnt(4)
	v_pk_mul_f32 v[30:31], v[30:31], v[50:51]
	v_pk_mul_f32 v[28:29], v[28:29], v[48:49]
	s_nop 1
	v_mfma_f32_16x16x32_bf16 v[28:31], v[214:217], v[44:47], v[28:31]
	s_waitcnt lgkmcnt(3)
	v_mfma_f32_16x16x32_bf16 v[28:31], v[218:221], v[36:39], v[28:31]
	s_waitcnt lgkmcnt(1)
	v_pk_mul_f32 v[34:35], v[34:35], v[224:225]
	v_pk_mul_f32 v[32:33], v[32:33], v[222:223]
	s_nop 1
	v_mfma_f32_16x16x32_bf16 v[32:35], v[226:229], v[44:47], v[32:35]
	s_waitcnt lgkmcnt(0)
	s_barrier
; #define LAS __attribute__((address_space(3)))
; #define MFMA16(a, b, c) __builtin_amdgcn_mfma_f32_16x16x32_bf16((a), (b), (c), 0, 0, 0)
; __device__ __forceinline__ void hgrn_r3(const GAS bf16* proj, const GAS float* RU, const GAS float* RD, GAS bf16* y, int TOKG, const GAS float* ogain, unsigned char* lds, int tid, int lane, int wave, int bid, int G) {
;     ...
; #pragma unroll
;             for (int t2 = 0; t2 < 4; ++t2)
; #pragma unroll
;                 for (int ks = 0; ks < 2; ++ks) { const bf16x8 af = *(const LAS bf16x8*)(L + H3_AM + (16 * t2 + fr) * HS + (32 * ks + 8 * fq) * 2); acc[t2] = MFMA16(vf[ks], af, acc[t2]); }
; #pragma unroll
;             for (int t2 = 0; t2 < 4; ++t2) { float ss = acc[t2][0] * acc[t2][0] + acc[t2][1] * acc[t2][1] + acc[t2][2] * acc[t2][2] + acc[t2][3] * acc[t2][3];
;                 ss += __shfl_xor(ss, 16); ss += __shfl_xor(ss, 32); if (fq == 0) red[(16 * t2 + fr) * 8 + wave] = ss; }
	v_mfma_f32_16x16x32_bf16 v[32:35], v[230:233], v[36:39], v[32:35]
	ds_read_b128 v[48:51], v132
	s_waitcnt lgkmcnt(0)
	v_mfma_f32_16x16x32_bf16 v[48:51], v[44:47], v[48:51], v[52:55]
	s_nop 2
	ds_read_b128 v[52:55], v132 offset:64
	s_waitcnt lgkmcnt(0)
	v_mfma_f32_16x16x32_bf16 v[64:67], v[36:39], v[52:55], v[48:51]
	ds_read_b128 v[52:55], v132 offset:2368
	s_nop 1
	ds_read_b128 v[48:51], v132 offset:2304
	s_waitcnt lgkmcnt(0)
	v_mfma_f32_16x16x32_bf16 v[48:51], v[44:47], v[48:51], v[56:59]
	s_nop 2
	ds_read_b128 v[56:59], v132 offset:4672
	v_mfma_f32_16x16x32_bf16 v[52:55], v[36:39], v[52:55], v[48:51]
	s_nop 2
	ds_read_b128 v[48:51], v132 offset:4608
	s_waitcnt lgkmcnt(0)
	v_mfma_f32_16x16x32_bf16 v[48:51], v[44:47], v[48:51], v[60:63]
	v_mfma_f32_16x16x32_bf16 v[48:51], v[36:39], v[56:59], v[48:51]
	ds_read_b128 v[56:59], v132 offset:6912
	s_waitcnt lgkmcnt(0)
	v_mfma_f32_16x16x32_bf16 v[40:43], v[44:47], v[56:59], v[40:43]
	ds_read_b128 v[44:47], v132 offset:6976
	s_waitcnt lgkmcnt(0)
	v_mfma_f32_16x16x32_bf16 v[36:39], v[36:39], v[44:47], v[40:43]
	s_nop 4
	v_mul_f32_e32 v214, v65, v65
	v_fmac_f32_e32 v214, v64, v64
	v_fmac_f32_e32 v214, v66, v66
	v_fmac_f32_e32 v214, v67, v67
	v_mul_f32_e32 v215, v53, v53
	v_fmac_f32_e32 v215, v52, v52
	v_fmac_f32_e32 v215, v54, v54
	v_fmac_f32_e32 v215, v55, v55
	v_mul_f32_e32 v216, v49, v49
	v_fmac_f32_e32 v216, v48, v48
	v_fmac_f32_e32 v216, v50, v50
	v_fmac_f32_e32 v216, v51, v51
	v_mul_f32_e32 v217, v37, v37
	v_fmac_f32_e32 v217, v36, v36
	v_fmac_f32_e32 v217, v38, v38
	v_fmac_f32_e32 v217, v39, v39
	ds_bpermute_b32 v218, v118, v214
	ds_bpermute_b32 v219, v118, v215
	ds_bpermute_b32 v220, v118, v216
	ds_bpermute_b32 v221, v118, v217
	s_waitcnt lgkmcnt(0)
	v_add_f32_e32 v214, v214, v218
	v_add_f32_e32 v215, v215, v219
	v_add_f32_e32 v216, v216, v220
	v_add_f32_e32 v217, v217, v221
	ds_bpermute_b32 v218, v119, v214
	ds_bpermute_b32 v219, v119, v215
	ds_bpermute_b32 v220, v119, v216
	ds_bpermute_b32 v221, v119, v217
	s_and_saveexec_b64 vcc, s[4:5]
	s_cbranch_execz .LBB0_383
	s_waitcnt lgkmcnt(0)
	v_add_f32_e32 v214, v214, v218
	v_add_f32_e32 v215, v215, v219
	v_add_f32_e32 v216, v216, v220
	v_add_f32_e32 v217, v217, v221
	ds_write_b32 v135, v214
	ds_write_b32 v135, v215 offset:512
	ds_write_b32 v135, v216 offset:1024
	ds_write_b32 v135, v217 offset:1536
	s_branch .LBB0_383
